# added grid-size guard in tail-convert slot entry (all WGs participate if grid <= nbusy); otherwise same as previous
# baseline (speedup 1.0000x reference)
; __device__ void phase_convert(PP p, unsigned char* smem) {
;     ...
;   int t = blockIdx.x;
;   if (t < NT_ALL) {
;     cvt_decode(p, t, src, ld, dst, K, k0, n0, n4);
; #pragma unroll
;     for (int i = 0; i < 4; ++i) cur[i] = src ? *(const f32x4*)(src + (size_t)(kl + 16 * i) * ld) : (f32x4){0.f, 0.f, 0.f, 0.f};
;   }
;   for (; t < NT_ALL; t += gridDim.x) {
;     const int tn = t + gridDim.x;
;     const float* src2 = nullptr; int ld2 = 0, K2, k02, n02; bf16_t* dst2;
.Lcvt_go:
	s_cmp_gt_u32 s60, s100
	s_cbranch_scc1 .Lcvt_gok
	s_mov_b32 s100, 0
